# in-proj tile order: column tile rotated inside each block of 4 by the block index (bijection), so every workgroup gets one q, k, v and gate tile (even epilogue cost)
# speedup vs baseline: 1.0798x; 1.0099x over previous
; #define PG8_STAGE(bufoff, gbase, voff) do { _Pragma("unroll") for (int _i = 0; _i < 2; ++_i) \
;         __builtin_amdgcn_global_load_lds((const unsigned*)((const char*)(gbase) + (voff)[_i]), (PG8_LAS unsigned*)(lds + (bufoff) + ldsw + _i * 8192), 16, 0, 0); } while (0)
; #define PG8_WAIT_V(n) asm volatile("s_waitcnt vmcnt(" #n ")" ::: "memory")
; #define PG8_BAR __builtin_amdgcn_s_barrier()
;     __host__ __device__ bool next(int i, Unit& u) const {
;     ...
;         int wgid = (int)L; { const int q = nwg / NXCD, r = nwg % NXCD, xcd = wgid % NXCD, off = wgid / NXCD; wgid = (xcd < r ? xcd * (q + 1) : r * (q + 1) + (xcd - r) * q) + off; }
;         const int nig = WGM * nN, gid = wgid / nig, fm = gid * WGM, gsz = (nM - fm) < WGM ? (nM - fm) : WGM;
;         u.pm = fm + ((wgid % nig) % gsz); u.pn = (wgid % nig) / gsz; return true;
; template <class Epi, class Sched, bool ALIGN_EPI = false, bool SP2 = false>
; __device__ __forceinline__ void gemm_phase(PG8_LAS unsigned char* lds, const Gemm g, const Sched& S, const Epi& E) {
;     ...
;     const char* cA = (const char*)g.A + (size_t)cur.pm * tstep; const char* cB = (const char*)g.Bt + (size_t)cur.pn * tstep;
;     S.a_ready(cur);
;     if constexpr (SP2) {
;         PG8_STAGE(PG8_SB(0, 0), cB, voffB); PG8_STAGE(PG8_SB(0, 1), cB + hstep, voffB); PG8_STAGE(PG8_SA(0, 0), cA, voffA); PG8_STAGE(PG8_SA(0, 1), cA + hstep, voffA);
;         if (wr == 1) PG8_BAR;
;         PG8_WAIT_V(2); PG8_BAR;
;         PG8_STAGE(PG8_SB(1, 0), cB + kstep, voffB); PG8_STAGE(PG8_SA(1, 0), cA + kstep, voffA); PG8_STAGE(PG8_SB(1, 1), cB + hstep + kstep, voffB);
;         PG8_WAIT_V(6); PG8_BAR;
.LBB0_129:
	s_lshr_b32 s1, s0, 2
	s_add_i32 s1, s1, s0
	s_and_b32 s1, s1, 3
	s_and_b32 s0, s0, 12
	s_or_b32 s0, s0, s1
	v_lshrrev_b32_e32 v3, 1, v138
	v_and_b32_e32 v10, 24, v3
	v_lshrrev_b32_e32 v3, 5, v138
	v_and_b32_e32 v3, 4, v3
	v_bfe_u32 v4, v138, 2, 2
	v_lshlrev_b32_e32 v1, 4, v138
	v_and_b32_e32 v2, 32, v138
	v_bfe_u32 v169, v138, 2, 4
	v_or3_b32 v3, v3, v4, v10
	v_lshrrev_b32_e32 v4, 3, v138
	s_movk_i32 s1, 0x70
	v_bitop3_b32 v139, v1, v2, 48 bitop3:0x6c
	v_and_b32_e32 v168, 64, v138
	v_and_or_b32 v5, v4, s1, v169
	s_movk_i32 s1, 0x60
	v_add_u32_e32 v170, 0x2000, v1
	v_or_b32_e32 v2, v139, v168
	v_and_or_b32 v4, v4, s1, v3
	v_lshrrev_b32_e32 v1, 7, v170
	s_movk_i32 s1, 0xf0
	v_lshl_or_b32 v142, v4, 11, v2
	v_and_or_b32 v4, v1, s1, v169
	s_movk_i32 s1, 0xe0
	v_and_or_b32 v1, v1, s1, v3
	v_lshl_or_b32 v146, v1, 11, v2
	v_lshlrev_b32_e32 v1, 6, v138
	v_lshlrev_b32_e32 v167, 2, v138
	v_lshl_or_b32 v140, v5, 11, v2
	v_lshl_or_b32 v144, v4, 11, v2
	v_and_b32_e32 v173, 15, v138
	v_and_b32_e32 v171, 0x3c0, v1
	s_andn2_b64 vcc, exec, s[4:5]
	v_and_b32_e32 v172, 32, v167
	s_cbranch_vccnz .LBB0_345
	s_lshr_b32 s15, s14, 6
	s_ashr_i32 s7, s6, 31
	s_ashr_i32 s1, s0, 31
	s_lshr_b32 s4, s14, 8
	s_lshl_b32 s23, s15, 10
	s_lshl_b64 s[8:9], s[6:7], 19
	s_lshl_b64 s[10:11], s[0:1], 19
	s_add_u32 s10, s62, s10
	s_addc_u32 s11, s63, s11
	s_add_i32 s42, s23, 0x100
	s_add_i32 m0, s42, 0x10000
	v_mov_b32_e32 v149, 0
	global_load_lds_dwordx4 v142, s[10:11]
	s_add_i32 m0, s42, 0x12000
	s_add_u32 s12, s10, 0x40000
	global_load_lds_dwordx4 v146, s[10:11]
	s_addc_u32 s13, s11, 0
	s_add_i32 m0, s42, 0x14000
	v_mov_b32_e32 v143, v149
	global_load_lds_dwordx4 v142, s[12:13]
	s_add_i32 m0, s42, 0x16000
	s_add_u32 s8, s66, s8
	s_addc_u32 s9, s67, s9
	s_add_i32 s43, s42, 0x2000
	global_load_lds_dwordx4 v146, s[12:13]
	s_mov_b32 m0, s42
	s_add_u32 s12, s8, 0x40000
	global_load_lds_dwordx4 v140, s[8:9]
	s_mov_b32 m0, s43
	s_addc_u32 s13, s9, 0
	s_add_i32 s46, s42, 0x4000
	global_load_lds_dwordx4 v144, s[8:9]
	s_mov_b32 m0, s46
	s_add_i32 s47, s42, 0x6000
	global_load_lds_dwordx4 v140, s[12:13]
	s_mov_b32 m0, s47
	v_mov_b32_e32 v147, v149
	global_load_lds_dwordx4 v144, s[12:13]
	v_mov_b32_e32 v141, v149
	v_mov_b32_e32 v145, v149
	s_cmp_eq_u32 s4, 1
	v_writelane_b32 v246, s94, 1
	s_mov_b32 s1, 0x10000
	v_lshl_add_u64 v[8:9], s[10:11], 0, v[142:143]
	v_lshl_add_u64 v[4:5], s[10:11], 0, v[146:147]
	s_mov_b32 s5, 0x14000
	v_lshl_add_u64 v[2:3], s[8:9], 0, v[140:141]
	s_cselect_b64 s[12:13], -1, 0
	s_cmp_lg_u32 s4, 1
	v_lshl_add_u64 v[6:7], s[8:9], 0, v[144:145]
	v_writelane_b32 v246, s95, 2
	s_cbranch_scc1 .LBB0_132
	s_barrier

; template <class Epi, class Sched, bool ALIGN_EPI = false, bool SP2 = false>
; __device__ __forceinline__ void gemm_phase(PG8_LAS unsigned char* lds, const Gemm g, const Sched& S, const Epi& E) {
;     ...
;         const bool has_next = S.next(ui + 1, nxt);
;         const char* nA = has_next ? (const char*)g.A + (size_t)nxt.pm * tstep : cA; const char* nB = has_next ? (const char*)g.Bt + (size_t)nxt.pn * tstep : cB;
;     ...
; #pragma unroll
;         for (int a = 0; a < 2; ++a)
; #pragma unroll
;             for (int b = 0; b < 2; ++b)
; #pragma unroll
;                 for (int m = 0; m < 4; ++m)
; #pragma unroll
;                     for (int n = 0; n < 2; ++n) acc[a][b][m][n] = (f32x4){0.f, 0.f, 0.f, 0.f};
;         cur = nxt; cA = nA; cB = nB; ++ui;
.LBB0_137:
	s_lshr_b32 s7, s24, 2
	s_add_i32 s7, s7, s24
	s_and_b32 s7, s7, 3
	s_and_b32 s24, s24, 12
	s_or_b32 s24, s24, s7
	s_ashr_i32 s27, s26, 31
	s_lshl_b64 s[28:29], s[26:27], 19
	s_add_u32 s28, s66, s28
	s_addc_u32 s29, s67, s29
	s_and_b64 s[30:31], s[4:5], exec
	s_cselect_b32 s1, s29, s9
	s_cselect_b32 s7, s28, s8
	s_ashr_i32 s25, s24, 31
	s_lshl_b64 s[30:31], s[24:25], 19
	s_add_u32 s30, s62, s30
	s_addc_u32 s31, s63, s31
	s_and_b64 s[34:35], s[4:5], exec
	s_cselect_b32 s15, s31, s11
	s_cselect_b32 s25, s30, s10
	s_add_u32 s8, s8, 0x40080
	s_addc_u32 s9, s9, 0
	s_add_u32 s27, s10, 0x100
	v_mov_b32_e32 v2, 0
	s_addc_u32 s36, s11, 0
	s_mov_b32 s37, -2
	v_mov_b32_e32 v3, v2
	v_mov_b32_e32 v4, v2
	v_mov_b32_e32 v5, v2
	v_mov_b32_e32 v6, v2
	v_mov_b32_e32 v7, v2
	v_mov_b32_e32 v8, v2
	v_mov_b32_e32 v9, v2
	v_mov_b32_e32 v18, v2
	v_mov_b32_e32 v19, v2
	v_mov_b32_e32 v20, v2
	v_mov_b32_e32 v21, v2
	v_mov_b32_e32 v22, v2
	v_mov_b32_e32 v23, v2
	v_mov_b32_e32 v24, v2
	v_mov_b32_e32 v25, v2
	v_mov_b32_e32 v34, v2
	v_mov_b32_e32 v35, v2
	v_mov_b32_e32 v36, v2
	v_mov_b32_e32 v37, v2
	v_mov_b32_e32 v38, v2
	v_mov_b32_e32 v39, v2
	v_mov_b32_e32 v40, v2
	v_mov_b32_e32 v41, v2
	v_mov_b32_e32 v50, v2
	v_mov_b32_e32 v51, v2
	v_mov_b32_e32 v52, v2
	v_mov_b32_e32 v53, v2
	v_mov_b32_e32 v54, v2
	v_mov_b32_e32 v55, v2
	v_mov_b32_e32 v56, v2
	v_mov_b32_e32 v57, v2
	v_mov_b32_e32 v10, v2
	v_mov_b32_e32 v11, v2
	v_mov_b32_e32 v12, v2
	v_mov_b32_e32 v13, v2
	v_mov_b32_e32 v14, v2
	v_mov_b32_e32 v15, v2
	v_mov_b32_e32 v16, v2
	v_mov_b32_e32 v17, v2
	v_mov_b32_e32 v26, v2
	v_mov_b32_e32 v27, v2
	v_mov_b32_e32 v28, v2
	v_mov_b32_e32 v29, v2
	v_mov_b32_e32 v30, v2
	v_mov_b32_e32 v31, v2
	v_mov_b32_e32 v32, v2
	v_mov_b32_e32 v33, v2
	v_mov_b32_e32 v42, v2
	v_mov_b32_e32 v43, v2
	v_mov_b32_e32 v44, v2
	v_mov_b32_e32 v45, v2
	v_mov_b32_e32 v46, v2
	v_mov_b32_e32 v47, v2
	v_mov_b32_e32 v48, v2
	v_mov_b32_e32 v49, v2
	v_mov_b32_e32 v58, v2
	v_mov_b32_e32 v59, v2
	v_mov_b32_e32 v60, v2
	v_mov_b32_e32 v61, v2
	v_mov_b32_e32 v62, v2
	v_mov_b32_e32 v63, v2
	v_mov_b32_e32 v64, v2
	v_mov_b32_e32 v65, v2
	v_mov_b32_e32 v66, v2
	v_mov_b32_e32 v67, v2
	v_mov_b32_e32 v68, v2
	v_mov_b32_e32 v69, v2
	v_mov_b32_e32 v70, v2
	v_mov_b32_e32 v71, v2
	v_mov_b32_e32 v72, v2
	v_mov_b32_e32 v73, v2
	v_mov_b32_e32 v82, v2
	v_mov_b32_e32 v83, v2
	v_mov_b32_e32 v84, v2
	v_mov_b32_e32 v85, v2
	v_mov_b32_e32 v86, v2
	v_mov_b32_e32 v87, v2
	v_mov_b32_e32 v88, v2
	v_mov_b32_e32 v89, v2
	v_mov_b32_e32 v98, v2
	v_mov_b32_e32 v99, v2
	v_mov_b32_e32 v100, v2
	v_mov_b32_e32 v101, v2
	v_mov_b32_e32 v102, v2
	v_mov_b32_e32 v103, v2
	v_mov_b32_e32 v104, v2
	v_mov_b32_e32 v105, v2
	v_mov_b32_e32 v114, v2
	v_mov_b32_e32 v115, v2
	v_mov_b32_e32 v116, v2
	v_mov_b32_e32 v117, v2
	v_mov_b32_e32 v118, v2
	v_mov_b32_e32 v119, v2
	v_mov_b32_e32 v120, v2
	v_mov_b32_e32 v121, v2
	v_mov_b32_e32 v74, v2
	v_mov_b32_e32 v75, v2
	v_mov_b32_e32 v76, v2
	v_mov_b32_e32 v77, v2
	v_mov_b32_e32 v78, v2
	v_mov_b32_e32 v79, v2
	v_mov_b32_e32 v80, v2
	v_mov_b32_e32 v81, v2
	v_mov_b32_e32 v90, v2
	v_mov_b32_e32 v91, v2
	v_mov_b32_e32 v92, v2
	v_mov_b32_e32 v93, v2
	v_mov_b32_e32 v94, v2
	v_mov_b32_e32 v95, v2
	v_mov_b32_e32 v96, v2
	v_mov_b32_e32 v97, v2
	v_mov_b32_e32 v106, v2
	v_mov_b32_e32 v107, v2
	v_mov_b32_e32 v108, v2
	v_mov_b32_e32 v109, v2
	v_mov_b32_e32 v110, v2
	v_mov_b32_e32 v111, v2
	v_mov_b32_e32 v112, v2
	v_mov_b32_e32 v113, v2
	v_mov_b32_e32 v122, v2
	v_mov_b32_e32 v123, v2
	v_mov_b32_e32 v124, v2
	v_mov_b32_e32 v125, v2
	v_mov_b32_e32 v126, v2
	v_mov_b32_e32 v127, v2
	v_mov_b32_e32 v128, v2
	v_mov_b32_e32 v129, v2
	s_cmp_eq_u32 s100, 15
	s_cbranch_scc0 .Lp1q_kloop
